# P1 GLU epilogue: the seven later row sum-of-squares loads issued at the top of the path, per-slice vmcnt(0) waits removed
# speedup vs baseline: 1.0073x; 1.0010x over previous
.LBB0_166:
	global_load_dword v217, v[168:169], off offset:64
	global_load_dword v218, v[168:169], off offset:128
	global_load_dword v219, v[168:169], off offset:192
	global_load_dword v220, v[168:169], off offset:512
	global_load_dword v221, v[168:169], off offset:576
	global_load_dword v222, v[168:169], off offset:640
	global_load_dword v223, v[168:169], off offset:704
	v_lshl_or_b32 v172, s55, 7, v183
	v_ashrrev_i32_e32 v173, 31, v172
	v_lshl_add_u64 v[130:131], v[172:173], 2, s[60:61]
	global_load_dwordx4 v[142:145], v[130:131], off offset:3072
	global_load_dwordx4 v[134:137], v[130:131], off offset:3088
	global_load_dwordx4 v[138:141], v[130:131], off
	s_nop 0
	global_load_dwordx4 v[130:133], v[130:131], off offset:16
	s_waitcnt vmcnt(3)
	v_fma_f32 v167, v122, v170, v142
	v_fma_f32 v190, v123, v170, v143
	s_waitcnt vmcnt(2)
	v_fma_f32 v189, v114, v170, v134
	s_waitcnt vmcnt(1)
	v_pk_fma_f32 v[122:123], v[126:127], v[170:171], v[138:139] op_sel_hi:[1,0,1]
	v_fma_f32 v126, v115, v170, v135
	s_waitcnt vmcnt(0)
	v_pk_fma_f32 v[114:115], v[118:119], v[170:171], v[130:131] op_sel_hi:[1,0,1]
	v_fma_f32 v124, v124, v170, v144
	v_fma_f32 v125, v125, v170, v145
	v_pk_fma_f32 v[118:119], v[128:129], v[170:171], v[140:141] op_sel_hi:[1,0,1]
	v_mul_f32_e32 v127, 0xbfb8aa3b, v167
	v_mul_f32_e32 v129, 0xbfb8aa3b, v190
	v_mul_f32_e32 v128, 0xbfb8aa3b, v189
	v_mul_f32_e32 v189, 0xbfb8aa3b, v124
	v_mul_f32_e32 v190, 0xbfb8aa3b, v125
	v_exp_f32_e32 v124, v127
	v_exp_f32_e32 v125, v129
	v_mul_f32_e32 v167, 0xbfb8aa3b, v126
	v_exp_f32_e32 v126, v128
	v_exp_f32_e32 v127, v167
	v_pk_add_f32 v[124:125], v[124:125], 1.0 op_sel_hi:[1,0]
	v_exp_f32_e32 v128, v189
	v_exp_f32_e32 v129, v190
	v_div_scale_f32 v167, s[0:1], v125, v125, 1.0
	v_pk_add_f32 v[126:127], v[126:127], 1.0 op_sel_hi:[1,0]
	v_div_scale_f32 v190, s[0:1], v124, v124, 1.0
	v_rcp_f32_e32 v201, v167
	v_div_scale_f32 v192, s[4:5], v127, v127, 1.0
	v_rcp_f32_e32 v202, v190
	v_div_scale_f32 v194, s[6:7], v126, v126, 1.0
	v_rcp_f32_e32 v203, v192
	v_pk_add_f32 v[128:129], v[128:129], 1.0 op_sel_hi:[1,0]
	v_rcp_f32_e32 v204, v194
	v_div_scale_f32 v196, s[8:9], v129, v129, 1.0
	v_fma_f32 v207, -v167, v201, 1.0
	v_div_scale_f32 v189, vcc, 1.0, v125, 1.0
	v_rcp_f32_e32 v205, v196
	v_fma_f32 v208, -v190, v202, 1.0
	v_fmac_f32_e32 v201, v207, v201
	v_div_scale_f32 v191, s[0:1], 1.0, v124, 1.0
	v_fma_f32 v209, -v192, v203, 1.0
	v_fmac_f32_e32 v202, v208, v202
	v_mul_f32_e32 v207, v189, v201
	v_div_scale_f32 v193, s[4:5], 1.0, v127, 1.0
	v_fma_f32 v210, -v194, v204, 1.0
	v_fmac_f32_e32 v203, v209, v203
	v_mul_f32_e32 v208, v191, v202
	v_fma_f32 v212, -v167, v207, v189
	v_div_scale_f32 v195, s[6:7], 1.0, v126, 1.0
	v_fmac_f32_e32 v204, v210, v204
	v_mul_f32_e32 v209, v193, v203
	v_fma_f32 v213, -v190, v208, v191
	v_fmac_f32_e32 v207, v212, v201
	v_fma_f32 v211, -v196, v205, 1.0
	v_mul_f32_e32 v210, v195, v204
	v_fma_f32 v214, -v192, v209, v193
	v_fmac_f32_e32 v208, v213, v202
	v_fma_f32 v167, -v167, v207, v189
	v_div_scale_f32 v197, s[8:9], 1.0, v129, 1.0
	v_fmac_f32_e32 v205, v211, v205
	v_fma_f32 v215, -v194, v210, v195
	v_fmac_f32_e32 v209, v214, v203
	v_fma_f32 v189, -v190, v208, v191
	v_div_fmas_f32 v167, v167, v201, v207
	s_mov_b64 vcc, s[0:1]
	v_div_scale_f32 v200, s[56:57], v128, v128, 1.0
	v_mul_f32_e32 v211, v197, v205
	v_fmac_f32_e32 v210, v215, v204
	v_fma_f32 v190, -v192, v209, v193
	v_div_fixup_f32 v125, v167, v125, 1.0
	v_div_fmas_f32 v167, v189, v202, v208
	s_mov_b64 vcc, s[4:5]
	v_rcp_f32_e32 v206, v200
	v_fma_f32 v216, -v196, v211, v197
	v_fma_f32 v191, -v194, v210, v195
	v_div_fixup_f32 v124, v167, v124, 1.0
	v_div_fmas_f32 v167, v190, v203, v209
	s_mov_b64 vcc, s[6:7]
	v_fmac_f32_e32 v211, v216, v205
	v_pk_mul_f32 v[122:123], v[122:123], v[124:125]
	v_div_fmas_f32 v124, v191, v204, v210
	v_fma_f32 v192, -v196, v211, v197
	v_div_fixup_f32 v125, v167, v127, 1.0
	v_div_fixup_f32 v124, v124, v126, 1.0
	s_mov_b64 vcc, s[8:9]
	v_fma_f32 v116, v116, v170, v136
	v_pk_mul_f32 v[114:115], v[114:115], v[124:125]
	v_div_fmas_f32 v124, v192, v205, v211
	v_fma_f32 v117, v117, v170, v137
	v_mul_f32_e32 v116, 0xbfb8aa3b, v116
	v_div_fixup_f32 v125, v124, v129, 1.0
	v_fma_f32 v124, -v200, v206, 1.0
	v_mul_f32_e32 v117, 0xbfb8aa3b, v117
	v_exp_f32_e32 v116, v116
	v_fmac_f32_e32 v206, v124, v206
	v_div_scale_f32 v124, vcc, 1.0, v128, 1.0
	v_exp_f32_e32 v117, v117
	v_mul_f32_e32 v126, v124, v206
	v_fma_f32 v127, -v200, v126, v124
	v_fmac_f32_e32 v126, v127, v206
	v_fma_f32 v124, -v200, v126, v124
	v_pk_add_f32 v[116:117], v[116:117], 1.0 op_sel_hi:[1,0]
	v_div_fmas_f32 v124, v124, v206, v126
	v_div_scale_f32 v126, s[0:1], v117, v117, 1.0
	v_rcp_f32_e32 v127, v126
	v_div_fixup_f32 v124, v124, v128, 1.0
	v_pk_mul_f32 v[124:125], v[118:119], v[124:125]
	v_pk_fma_f32 v[118:119], v[120:121], v[170:171], v[132:133] op_sel_hi:[1,0,1]
	v_fma_f32 v120, -v126, v127, 1.0
	v_fmac_f32_e32 v127, v120, v127
	v_div_scale_f32 v120, vcc, 1.0, v117, 1.0
	v_mul_f32_e32 v121, v120, v127
	v_fma_f32 v128, -v126, v121, v120
	v_fmac_f32_e32 v121, v128, v127
	v_fma_f32 v120, -v126, v121, v120
	v_div_scale_f32 v126, s[0:1], v116, v116, 1.0
	v_rcp_f32_e32 v128, v126
	v_div_fmas_f32 v120, v120, v127, v121
	v_div_fixup_f32 v117, v120, v117, 1.0
	v_fma_f32 v120, -v126, v128, 1.0
	v_fmac_f32_e32 v128, v120, v128
	v_div_scale_f32 v120, vcc, 1.0, v116, 1.0
	v_mul_f32_e32 v121, v120, v128
	v_fma_f32 v127, -v126, v121, v120
	v_fmac_f32_e32 v121, v127, v128
	v_fma_f32 v120, -v126, v121, v120
	v_div_fmas_f32 v120, v120, v128, v121
	v_div_fixup_f32 v116, v120, v116, 1.0
	v_pk_mul_f32 v[116:117], v[118:119], v[116:117]
	v_cvt_pk_bf16_f32 v120, v114, v115
	v_mov_b64_e32 v[114:115], s[38:39]
	v_cvt_pk_bf16_f32 v118, v122, v123
	v_cvt_pk_bf16_f32 v121, v116, v117
	v_mad_i64_i32 v[122:123], s[0:1], v166, s54, v[114:115]
	v_lshlrev_b64 v[116:117], 1, v[172:173]
	v_cvt_pk_bf16_f32 v119, v124, v125
	v_lshl_add_u64 v[122:123], v[122:123], 0, v[116:117]
	global_store_dwordx4 v[122:123], v[118:121], off
	s_nop 1
	v_or_b32_e32 v118, 16, v166
	v_ashrrev_i32_e32 v119, 31, v118
	v_lshl_add_u64 v[120:121], v[118:119], 2, s[16:17]
	s_nop 1
	v_mov_b32_e32 v119, v217
	v_fmamk_f32 v119, v119, 0x3a800000, v187
	v_rsq_f32_e32 v120, v119
	s_nop 0
	v_fma_f32 v106, v106, v120, v142
	v_fma_f32 v107, v107, v120, v143
	v_fma_f32 v98, v98, v120, v134
	v_fma_f32 v99, v99, v120, v135
	v_mul_f32_e32 v106, 0xbfb8aa3b, v106
	v_mul_f32_e32 v107, 0xbfb8aa3b, v107
	v_mul_f32_e32 v119, 0xbfb8aa3b, v98
	v_mul_f32_e32 v121, 0xbfb8aa3b, v99
	v_exp_f32_e32 v98, v106
	v_exp_f32_e32 v99, v107
	v_exp_f32_e32 v106, v119
	v_exp_f32_e32 v107, v121
	v_pk_fma_f32 v[110:111], v[110:111], v[120:121], v[138:139] op_sel_hi:[1,0,1]
	v_pk_add_f32 v[98:99], v[98:99], 1.0 op_sel_hi:[1,0]
	v_pk_fma_f32 v[102:103], v[102:103], v[120:121], v[130:131] op_sel_hi:[1,0,1]
	v_div_scale_f32 v119, s[0:1], v99, v99, 1.0
	v_div_scale_f32 v122, s[0:1], v98, v98, 1.0
	v_rcp_f32_e32 v124, v119
	v_rcp_f32_e32 v125, v122
	v_pk_add_f32 v[106:107], v[106:107], 1.0 op_sel_hi:[1,0]
	v_div_scale_f32 v121, vcc, 1.0, v99, 1.0
	v_fma_f32 v128, -v119, v124, 1.0
	v_div_scale_f32 v123, s[0:1], v107, v107, 1.0
	v_fma_f32 v129, -v122, v125, 1.0
	v_fmac_f32_e32 v124, v128, v124
	v_div_scale_f32 v127, s[0:1], 1.0, v98, 1.0
	v_fmac_f32_e32 v125, v129, v125
	v_mul_f32_e32 v128, v121, v124
	v_mul_f32_e32 v129, v127, v125
	v_fma_f32 v170, -v119, v128, v121
	v_rcp_f32_e32 v126, v123
	v_fma_f32 v172, -v122, v129, v127
	v_fmac_f32_e32 v128, v170, v124
	v_fmac_f32_e32 v129, v172, v125
	v_fma_f32 v119, -v119, v128, v121
	v_fma_f32 v121, -v122, v129, v127
	v_div_fmas_f32 v119, v119, v124, v128
	s_mov_b64 vcc, s[0:1]
	v_div_fixup_f32 v99, v119, v99, 1.0
	v_div_fmas_f32 v119, v121, v125, v129
	v_fma_f32 v167, -v123, v126, 1.0
	v_div_fixup_f32 v98, v119, v98, 1.0
	v_pk_mul_f32 v[98:99], v[110:111], v[98:99]
	v_fmac_f32_e32 v126, v167, v126
	v_div_scale_f32 v110, vcc, 1.0, v107, 1.0
	v_mul_f32_e32 v111, v110, v126
	v_fma_f32 v119, -v123, v111, v110
	v_fmac_f32_e32 v111, v119, v126
	v_div_scale_f32 v119, s[0:1], v106, v106, 1.0
	v_rcp_f32_e32 v121, v119
	v_fma_f32 v110, -v123, v111, v110
	v_div_fmas_f32 v110, v110, v126, v111
	v_div_fixup_f32 v107, v110, v107, 1.0
	v_fma_f32 v110, -v119, v121, 1.0
	v_fmac_f32_e32 v121, v110, v121
	v_div_scale_f32 v110, vcc, 1.0, v106, 1.0
	v_mul_f32_e32 v111, v110, v121
	v_fma_f32 v108, v108, v120, v144
	v_fma_f32 v109, v109, v120, v145
	v_fma_f32 v122, -v119, v111, v110
	v_mul_f32_e32 v108, 0xbfb8aa3b, v108
	v_mul_f32_e32 v109, 0xbfb8aa3b, v109
	v_fmac_f32_e32 v111, v122, v121
	v_exp_f32_e32 v108, v108
	v_exp_f32_e32 v109, v109
	v_fma_f32 v110, -v119, v111, v110
	v_div_fmas_f32 v110, v110, v121, v111
	v_div_fixup_f32 v106, v110, v106, 1.0
	v_pk_mul_f32 v[102:103], v[102:103], v[106:107]
	v_pk_add_f32 v[106:107], v[108:109], 1.0 op_sel_hi:[1,0]
	v_pk_fma_f32 v[108:109], v[112:113], v[120:121], v[140:141] op_sel_hi:[1,0,1]
	v_div_scale_f32 v110, s[0:1], v107, v107, 1.0
	v_rcp_f32_e32 v111, v110
	v_fma_f32 v100, v100, v120, v136
	v_fma_f32 v101, v101, v120, v137
	v_mul_f32_e32 v100, 0xbfb8aa3b, v100
	v_fma_f32 v112, -v110, v111, 1.0
	v_fmac_f32_e32 v111, v112, v111
	v_div_scale_f32 v112, vcc, 1.0, v107, 1.0
	v_mul_f32_e32 v113, v112, v111
	v_fma_f32 v119, -v110, v113, v112
	v_fmac_f32_e32 v113, v119, v111
	v_fma_f32 v110, -v110, v113, v112
	v_div_scale_f32 v112, s[0:1], v106, v106, 1.0
	v_rcp_f32_e32 v119, v112
	v_div_fmas_f32 v110, v110, v111, v113
	v_div_fixup_f32 v107, v110, v107, 1.0
	v_mul_f32_e32 v101, 0xbfb8aa3b, v101
	v_fma_f32 v110, -v112, v119, 1.0
	v_exp_f32_e32 v100, v100
	v_fmac_f32_e32 v119, v110, v119
	v_div_scale_f32 v110, vcc, 1.0, v106, 1.0
	v_exp_f32_e32 v101, v101
	v_mul_f32_e32 v111, v110, v119
	v_fma_f32 v113, -v112, v111, v110
	v_fmac_f32_e32 v111, v113, v119
	v_fma_f32 v110, -v112, v111, v110
	v_pk_add_f32 v[100:101], v[100:101], 1.0 op_sel_hi:[1,0]
	v_div_fmas_f32 v110, v110, v119, v111
	v_div_scale_f32 v111, s[0:1], v101, v101, 1.0
	v_rcp_f32_e32 v112, v111
	v_div_fixup_f32 v106, v110, v106, 1.0
	v_pk_mul_f32 v[106:107], v[108:109], v[106:107]
	v_pk_fma_f32 v[104:105], v[104:105], v[120:121], v[132:133] op_sel_hi:[1,0,1]
	v_fma_f32 v108, -v111, v112, 1.0
	v_fmac_f32_e32 v112, v108, v112
	v_div_scale_f32 v108, vcc, 1.0, v101, 1.0
	v_mul_f32_e32 v109, v108, v112
	v_fma_f32 v110, -v111, v109, v108
	v_fmac_f32_e32 v109, v110, v112
	v_div_scale_f32 v110, s[0:1], v100, v100, 1.0
	v_fma_f32 v108, -v111, v109, v108
	v_rcp_f32_e32 v111, v110
	v_div_fmas_f32 v108, v108, v112, v109
	v_div_fixup_f32 v101, v108, v101, 1.0
	v_cvt_pk_bf16_f32 v98, v98, v99
	v_fma_f32 v108, -v110, v111, 1.0
	v_fmac_f32_e32 v111, v108, v111
	v_div_scale_f32 v108, vcc, 1.0, v100, 1.0
	v_mul_f32_e32 v109, v108, v111
	v_fma_f32 v112, -v110, v109, v108
	v_fmac_f32_e32 v109, v112, v111
	v_fma_f32 v108, -v110, v109, v108
	v_div_fmas_f32 v108, v108, v111, v109
	v_div_fixup_f32 v100, v108, v100, 1.0
	v_pk_mul_f32 v[104:105], v[104:105], v[100:101]
	v_cvt_pk_bf16_f32 v100, v102, v103
	v_mad_i64_i32 v[102:103], s[0:1], v118, s54, v[114:115]
	v_cvt_pk_bf16_f32 v99, v106, v107
	v_cvt_pk_bf16_f32 v101, v104, v105
	v_lshl_add_u64 v[102:103], v[102:103], 0, v[116:117]
	global_store_dwordx4 v[102:103], v[98:101], off
	s_nop 1
	v_or_b32_e32 v98, 32, v166
	v_ashrrev_i32_e32 v99, 31, v98
	v_lshl_add_u64 v[100:101], v[98:99], 2, s[16:17]
	s_nop 1
	v_mov_b32_e32 v99, v218
	v_fmamk_f32 v99, v99, 0x3a800000, v187
	v_rsq_f32_e32 v100, v99
	s_nop 0
	v_fma_f32 v90, v90, v100, v142
	v_fma_f32 v91, v91, v100, v143
	v_mul_f32_e32 v90, 0xbfb8aa3b, v90
	v_mul_f32_e32 v91, 0xbfb8aa3b, v91
	v_exp_f32_e32 v90, v90
	v_exp_f32_e32 v91, v91
	v_fma_f32 v82, v82, v100, v134
	v_fma_f32 v83, v83, v100, v135
	v_mul_f32_e32 v82, 0xbfb8aa3b, v82
	v_pk_add_f32 v[90:91], v[90:91], 1.0 op_sel_hi:[1,0]
	v_mul_f32_e32 v83, 0xbfb8aa3b, v83
	v_div_scale_f32 v99, s[0:1], v91, v91, 1.0
	v_rcp_f32_e32 v101, v99
	v_exp_f32_e32 v82, v82
	v_exp_f32_e32 v83, v83
	v_fma_f32 v92, v92, v100, v144
	v_fma_f32 v102, -v99, v101, 1.0
	v_pk_fma_f32 v[94:95], v[94:95], v[100:101], v[138:139] op_sel_hi:[1,0,1]
	v_fmac_f32_e32 v101, v102, v101
	v_div_scale_f32 v102, vcc, 1.0, v91, 1.0
	v_mul_f32_e32 v103, v102, v101
	v_fma_f32 v104, -v99, v103, v102
	v_fmac_f32_e32 v103, v104, v101
	v_fma_f32 v99, -v99, v103, v102
	v_div_scale_f32 v102, s[0:1], v90, v90, 1.0
	v_rcp_f32_e32 v104, v102
	v_div_fmas_f32 v99, v99, v101, v103
	v_div_fixup_f32 v91, v99, v91, 1.0
	v_pk_add_f32 v[82:83], v[82:83], 1.0 op_sel_hi:[1,0]
	v_fma_f32 v99, -v102, v104, 1.0
	v_fmac_f32_e32 v104, v99, v104
	v_div_scale_f32 v99, vcc, 1.0, v90, 1.0
	v_mul_f32_e32 v101, v99, v104
	v_fma_f32 v103, -v102, v101, v99
	v_fmac_f32_e32 v101, v103, v104
	v_fma_f32 v99, -v102, v101, v99
	v_div_fmas_f32 v99, v99, v104, v101
	v_div_scale_f32 v101, s[0:1], v83, v83, 1.0
	v_rcp_f32_e32 v102, v101
	v_div_fixup_f32 v90, v99, v90, 1.0
	v_pk_mul_f32 v[90:91], v[94:95], v[90:91]
	v_pk_fma_f32 v[86:87], v[86:87], v[100:101], v[130:131] op_sel_hi:[1,0,1]
	v_fma_f32 v94, -v101, v102, 1.0
	v_fmac_f32_e32 v102, v94, v102
	v_div_scale_f32 v94, vcc, 1.0, v83, 1.0
	v_mul_f32_e32 v95, v94, v102
	v_fma_f32 v99, -v101, v95, v94
	v_fmac_f32_e32 v95, v99, v102
	v_div_scale_f32 v99, s[0:1], v82, v82, 1.0
	v_fma_f32 v94, -v101, v95, v94
	v_rcp_f32_e32 v101, v99
	v_div_fmas_f32 v94, v94, v102, v95
	v_div_fixup_f32 v83, v94, v83, 1.0
	v_fma_f32 v93, v93, v100, v145
	v_fma_f32 v94, -v99, v101, 1.0
	v_fmac_f32_e32 v101, v94, v101
	v_div_scale_f32 v94, vcc, 1.0, v82, 1.0
	v_mul_f32_e32 v95, v94, v101
	v_fma_f32 v102, -v99, v95, v94
	v_mul_f32_e32 v92, 0xbfb8aa3b, v92
	v_mul_f32_e32 v93, 0xbfb8aa3b, v93
	v_fmac_f32_e32 v95, v102, v101
	v_exp_f32_e32 v92, v92
	v_exp_f32_e32 v93, v93
	v_fma_f32 v94, -v99, v95, v94
	v_div_fmas_f32 v94, v94, v101, v95
	v_div_fixup_f32 v82, v94, v82, 1.0
	v_pk_mul_f32 v[86:87], v[86:87], v[82:83]
	v_pk_add_f32 v[82:83], v[92:93], 1.0 op_sel_hi:[1,0]
	v_pk_fma_f32 v[92:93], v[96:97], v[100:101], v[140:141] op_sel_hi:[1,0,1]
	v_div_scale_f32 v94, s[0:1], v83, v83, 1.0
	v_rcp_f32_e32 v95, v94
	v_fma_f32 v84, v84, v100, v136
	v_fma_f32 v85, v85, v100, v137
	v_mul_f32_e32 v84, 0xbfb8aa3b, v84
	v_fma_f32 v96, -v94, v95, 1.0
	v_fmac_f32_e32 v95, v96, v95
	v_div_scale_f32 v96, vcc, 1.0, v83, 1.0
	v_mul_f32_e32 v97, v96, v95
	v_fma_f32 v99, -v94, v97, v96
	v_fmac_f32_e32 v97, v99, v95
	v_fma_f32 v94, -v94, v97, v96
	v_div_scale_f32 v96, s[0:1], v82, v82, 1.0
	v_rcp_f32_e32 v99, v96
	v_div_fmas_f32 v94, v94, v95, v97
	v_div_fixup_f32 v83, v94, v83, 1.0
	v_mul_f32_e32 v85, 0xbfb8aa3b, v85
	v_fma_f32 v94, -v96, v99, 1.0
	v_exp_f32_e32 v84, v84
	v_fmac_f32_e32 v99, v94, v99
	v_div_scale_f32 v94, vcc, 1.0, v82, 1.0
	v_exp_f32_e32 v85, v85
	v_mul_f32_e32 v95, v94, v99
	v_fma_f32 v97, -v96, v95, v94
	v_fmac_f32_e32 v95, v97, v99
	v_fma_f32 v94, -v96, v95, v94
	v_pk_add_f32 v[84:85], v[84:85], 1.0 op_sel_hi:[1,0]
	v_div_fmas_f32 v94, v94, v99, v95
	v_div_scale_f32 v95, s[0:1], v85, v85, 1.0
	v_rcp_f32_e32 v96, v95
	v_div_fixup_f32 v82, v94, v82, 1.0
	v_pk_mul_f32 v[92:93], v[92:93], v[82:83]
	v_pk_fma_f32 v[82:83], v[88:89], v[100:101], v[132:133] op_sel_hi:[1,0,1]
	v_fma_f32 v88, -v95, v96, 1.0
	v_fmac_f32_e32 v96, v88, v96
	v_div_scale_f32 v88, vcc, 1.0, v85, 1.0
	v_mul_f32_e32 v89, v88, v96
	v_fma_f32 v94, -v95, v89, v88
	v_fmac_f32_e32 v89, v94, v96
	v_div_scale_f32 v94, s[0:1], v84, v84, 1.0
	v_fma_f32 v88, -v95, v89, v88
	v_rcp_f32_e32 v95, v94
	v_div_fmas_f32 v88, v88, v96, v89
	v_div_fixup_f32 v85, v88, v85, 1.0
	v_fma_f32 v88, -v94, v95, 1.0
	v_fmac_f32_e32 v95, v88, v95
	v_div_scale_f32 v88, vcc, 1.0, v84, 1.0
	v_mul_f32_e32 v89, v88, v95
	v_fma_f32 v96, -v94, v89, v88
	v_fmac_f32_e32 v89, v96, v95
	v_fma_f32 v88, -v94, v89, v88
	v_div_fmas_f32 v88, v88, v95, v89
	v_div_fixup_f32 v84, v88, v84, 1.0
	v_pk_mul_f32 v[88:89], v[82:83], v[84:85]
	v_cvt_pk_bf16_f32 v84, v86, v87
	v_mad_i64_i32 v[86:87], s[0:1], v98, s54, v[114:115]
	v_cvt_pk_bf16_f32 v82, v90, v91
	v_cvt_pk_bf16_f32 v83, v92, v93
	v_cvt_pk_bf16_f32 v85, v88, v89
	v_lshl_add_u64 v[86:87], v[86:87], 0, v[116:117]
	global_store_dwordx4 v[86:87], v[82:85], off
	s_nop 1
	v_or_b32_e32 v82, 48, v166
	v_ashrrev_i32_e32 v83, 31, v82
	v_lshl_add_u64 v[84:85], v[82:83], 2, s[16:17]
	s_nop 1
	v_mov_b32_e32 v83, v219
	v_fmamk_f32 v83, v83, 0x3a800000, v187
	v_rsq_f32_e32 v84, v83
	s_nop 0
	v_fma_f32 v74, v74, v84, v142
	v_fma_f32 v75, v75, v84, v143
	v_mul_f32_e32 v74, 0xbfb8aa3b, v74
	v_mul_f32_e32 v75, 0xbfb8aa3b, v75
	v_exp_f32_e32 v74, v74
	v_exp_f32_e32 v75, v75
	v_fma_f32 v66, v66, v84, v134
	v_fma_f32 v67, v67, v84, v135
	v_mul_f32_e32 v66, 0xbfb8aa3b, v66
	v_pk_add_f32 v[74:75], v[74:75], 1.0 op_sel_hi:[1,0]
	v_mul_f32_e32 v67, 0xbfb8aa3b, v67
	v_div_scale_f32 v83, s[0:1], v75, v75, 1.0
	v_rcp_f32_e32 v85, v83
	v_exp_f32_e32 v66, v66
	v_exp_f32_e32 v67, v67
	v_fma_f32 v76, v76, v84, v144
	v_fma_f32 v86, -v83, v85, 1.0
	v_pk_fma_f32 v[78:79], v[78:79], v[84:85], v[138:139] op_sel_hi:[1,0,1]
	v_fmac_f32_e32 v85, v86, v85
	v_div_scale_f32 v86, vcc, 1.0, v75, 1.0
	v_mul_f32_e32 v87, v86, v85
	v_fma_f32 v88, -v83, v87, v86
	v_fmac_f32_e32 v87, v88, v85
	v_fma_f32 v83, -v83, v87, v86
	v_div_scale_f32 v86, s[0:1], v74, v74, 1.0
	v_rcp_f32_e32 v88, v86
	v_div_fmas_f32 v83, v83, v85, v87
	v_div_fixup_f32 v75, v83, v75, 1.0
	v_pk_add_f32 v[66:67], v[66:67], 1.0 op_sel_hi:[1,0]
	v_fma_f32 v83, -v86, v88, 1.0
	v_fmac_f32_e32 v88, v83, v88
	v_div_scale_f32 v83, vcc, 1.0, v74, 1.0
	v_mul_f32_e32 v85, v83, v88
	v_fma_f32 v87, -v86, v85, v83
	v_fmac_f32_e32 v85, v87, v88
	v_fma_f32 v83, -v86, v85, v83
	v_div_fmas_f32 v83, v83, v88, v85
	v_div_scale_f32 v85, s[0:1], v67, v67, 1.0
	v_rcp_f32_e32 v86, v85
	v_div_fixup_f32 v74, v83, v74, 1.0
	v_pk_mul_f32 v[74:75], v[78:79], v[74:75]
	v_pk_fma_f32 v[70:71], v[70:71], v[84:85], v[130:131] op_sel_hi:[1,0,1]
	v_fma_f32 v78, -v85, v86, 1.0
	v_fmac_f32_e32 v86, v78, v86
	v_div_scale_f32 v78, vcc, 1.0, v67, 1.0
	v_mul_f32_e32 v79, v78, v86
	v_fma_f32 v83, -v85, v79, v78
	v_fmac_f32_e32 v79, v83, v86
	v_div_scale_f32 v83, s[0:1], v66, v66, 1.0
	v_fma_f32 v78, -v85, v79, v78
	v_rcp_f32_e32 v85, v83
	v_div_fmas_f32 v78, v78, v86, v79
	v_div_fixup_f32 v67, v78, v67, 1.0
	v_fma_f32 v77, v77, v84, v145
	v_fma_f32 v78, -v83, v85, 1.0
	v_fmac_f32_e32 v85, v78, v85
	v_div_scale_f32 v78, vcc, 1.0, v66, 1.0
	v_mul_f32_e32 v79, v78, v85
	v_fma_f32 v86, -v83, v79, v78
	v_mul_f32_e32 v76, 0xbfb8aa3b, v76
	v_mul_f32_e32 v77, 0xbfb8aa3b, v77
	v_fmac_f32_e32 v79, v86, v85
	v_exp_f32_e32 v76, v76
	v_exp_f32_e32 v77, v77
	v_fma_f32 v78, -v83, v79, v78
	v_div_fmas_f32 v78, v78, v85, v79
	v_div_fixup_f32 v66, v78, v66, 1.0
	v_pk_mul_f32 v[70:71], v[70:71], v[66:67]
	v_pk_add_f32 v[66:67], v[76:77], 1.0 op_sel_hi:[1,0]
	v_pk_fma_f32 v[76:77], v[80:81], v[84:85], v[140:141] op_sel_hi:[1,0,1]
	v_div_scale_f32 v78, s[0:1], v67, v67, 1.0
	v_rcp_f32_e32 v79, v78
	v_fma_f32 v68, v68, v84, v136
	v_fma_f32 v69, v69, v84, v137
	v_mul_f32_e32 v68, 0xbfb8aa3b, v68
	v_fma_f32 v80, -v78, v79, 1.0
	v_fmac_f32_e32 v79, v80, v79
	v_div_scale_f32 v80, vcc, 1.0, v67, 1.0
	v_mul_f32_e32 v81, v80, v79
	v_fma_f32 v83, -v78, v81, v80
	v_fmac_f32_e32 v81, v83, v79
	v_fma_f32 v78, -v78, v81, v80
	v_div_scale_f32 v80, s[0:1], v66, v66, 1.0
	v_rcp_f32_e32 v83, v80
	v_div_fmas_f32 v78, v78, v79, v81
	v_div_fixup_f32 v67, v78, v67, 1.0
	v_mul_f32_e32 v69, 0xbfb8aa3b, v69
	v_fma_f32 v78, -v80, v83, 1.0
	v_exp_f32_e32 v68, v68
	v_fmac_f32_e32 v83, v78, v83
	v_div_scale_f32 v78, vcc, 1.0, v66, 1.0
	v_exp_f32_e32 v69, v69
	v_mul_f32_e32 v79, v78, v83
	v_fma_f32 v81, -v80, v79, v78
	v_fmac_f32_e32 v79, v81, v83
	v_fma_f32 v78, -v80, v79, v78
	v_pk_add_f32 v[68:69], v[68:69], 1.0 op_sel_hi:[1,0]
	v_div_fmas_f32 v78, v78, v83, v79
	v_div_scale_f32 v79, s[0:1], v69, v69, 1.0
	v_rcp_f32_e32 v80, v79
	v_div_fixup_f32 v66, v78, v66, 1.0
	v_pk_mul_f32 v[76:77], v[76:77], v[66:67]
	v_pk_fma_f32 v[66:67], v[72:73], v[84:85], v[132:133] op_sel_hi:[1,0,1]
	v_fma_f32 v72, -v79, v80, 1.0
	v_fmac_f32_e32 v80, v72, v80
	v_div_scale_f32 v72, vcc, 1.0, v69, 1.0
	v_mul_f32_e32 v73, v72, v80
	v_fma_f32 v78, -v79, v73, v72
	v_fmac_f32_e32 v73, v78, v80
	v_div_scale_f32 v78, s[0:1], v68, v68, 1.0
	v_fma_f32 v72, -v79, v73, v72
	v_rcp_f32_e32 v79, v78
	v_div_fmas_f32 v72, v72, v80, v73
	v_div_fixup_f32 v69, v72, v69, 1.0
	v_fma_f32 v72, -v78, v79, 1.0
	v_fmac_f32_e32 v79, v72, v79
	v_div_scale_f32 v72, vcc, 1.0, v68, 1.0
	v_mul_f32_e32 v73, v72, v79
	v_fma_f32 v80, -v78, v73, v72
	v_fmac_f32_e32 v73, v80, v79
	v_fma_f32 v72, -v78, v73, v72
	v_div_fmas_f32 v72, v72, v79, v73
	v_div_fixup_f32 v68, v72, v68, 1.0
	v_pk_mul_f32 v[72:73], v[66:67], v[68:69]
	v_cvt_pk_bf16_f32 v68, v70, v71
	v_mad_i64_i32 v[70:71], s[0:1], v82, s54, v[114:115]
	v_cvt_pk_bf16_f32 v66, v74, v75
	v_cvt_pk_bf16_f32 v67, v76, v77
	v_cvt_pk_bf16_f32 v69, v72, v73
	v_lshl_add_u64 v[70:71], v[70:71], 0, v[116:117]
	global_store_dwordx4 v[70:71], v[66:69], off
	s_nop 1
	v_mov_b32_e32 v66, v220
	s_nop 0
	v_add_u32_e32 v67, 0x80, v166
	v_fmamk_f32 v66, v66, 0x3a800000, v187
	v_rsq_f32_e32 v66, v66
	s_nop 0
	v_fma_f32 v58, v58, v66, v142
	v_fma_f32 v59, v59, v66, v143
	v_mul_f32_e32 v58, 0xbfb8aa3b, v58
	v_mul_f32_e32 v59, 0xbfb8aa3b, v59
	v_exp_f32_e32 v58, v58
	v_exp_f32_e32 v59, v59
	v_fma_f32 v50, v50, v66, v134
	v_fma_f32 v51, v51, v66, v135
	v_mul_f32_e32 v50, 0xbfb8aa3b, v50
	v_pk_add_f32 v[58:59], v[58:59], 1.0 op_sel_hi:[1,0]
	v_mul_f32_e32 v51, 0xbfb8aa3b, v51
	v_div_scale_f32 v68, s[0:1], v59, v59, 1.0
	v_rcp_f32_e32 v69, v68
	v_exp_f32_e32 v50, v50
	v_exp_f32_e32 v51, v51
	v_pk_fma_f32 v[62:63], v[62:63], v[66:67], v[138:139] op_sel_hi:[1,0,1]
	v_fma_f32 v70, -v68, v69, 1.0
	v_fmac_f32_e32 v69, v70, v69
	v_div_scale_f32 v70, vcc, 1.0, v59, 1.0
	v_mul_f32_e32 v71, v70, v69
	v_fma_f32 v72, -v68, v71, v70
	v_fmac_f32_e32 v71, v72, v69
	v_fma_f32 v68, -v68, v71, v70
	v_div_scale_f32 v70, s[0:1], v58, v58, 1.0
	v_rcp_f32_e32 v72, v70
	v_div_fmas_f32 v68, v68, v69, v71
	v_div_fixup_f32 v59, v68, v59, 1.0
	v_pk_add_f32 v[50:51], v[50:51], 1.0 op_sel_hi:[1,0]
	v_fma_f32 v68, -v70, v72, 1.0
	v_fmac_f32_e32 v72, v68, v72
	v_div_scale_f32 v68, vcc, 1.0, v58, 1.0
	v_mul_f32_e32 v69, v68, v72
	v_fma_f32 v71, -v70, v69, v68
	v_fmac_f32_e32 v69, v71, v72
	v_fma_f32 v68, -v70, v69, v68
	v_div_fmas_f32 v68, v68, v72, v69
	v_div_scale_f32 v69, s[0:1], v51, v51, 1.0
	v_rcp_f32_e32 v70, v69
	v_div_fixup_f32 v58, v68, v58, 1.0
	v_pk_mul_f32 v[58:59], v[62:63], v[58:59]
	v_fma_f32 v60, v60, v66, v144
	v_fma_f32 v62, -v69, v70, 1.0
	v_fmac_f32_e32 v70, v62, v70
	v_div_scale_f32 v62, vcc, 1.0, v51, 1.0
	v_mul_f32_e32 v63, v62, v70
	v_fma_f32 v68, -v69, v63, v62
	v_fmac_f32_e32 v63, v68, v70
	v_div_scale_f32 v68, s[0:1], v50, v50, 1.0
	v_fma_f32 v62, -v69, v63, v62
	v_rcp_f32_e32 v69, v68
	v_div_fmas_f32 v62, v62, v70, v63
	v_div_fixup_f32 v51, v62, v51, 1.0
	v_fma_f32 v61, v61, v66, v145
	v_fma_f32 v62, -v68, v69, 1.0
	v_fmac_f32_e32 v69, v62, v69
	v_div_scale_f32 v62, vcc, 1.0, v50, 1.0
	v_mul_f32_e32 v63, v62, v69
	v_fma_f32 v70, -v68, v63, v62
	v_mul_f32_e32 v60, 0xbfb8aa3b, v60
	v_mul_f32_e32 v61, 0xbfb8aa3b, v61
	v_fmac_f32_e32 v63, v70, v69
	v_exp_f32_e32 v60, v60
	v_exp_f32_e32 v61, v61
	v_fma_f32 v62, -v68, v63, v62
	v_div_fmas_f32 v62, v62, v69, v63
	v_pk_fma_f32 v[54:55], v[54:55], v[66:67], v[130:131] op_sel_hi:[1,0,1]
	v_div_fixup_f32 v50, v62, v50, 1.0
	v_pk_mul_f32 v[54:55], v[54:55], v[50:51]
	v_pk_add_f32 v[50:51], v[60:61], 1.0 op_sel_hi:[1,0]
	v_pk_fma_f32 v[60:61], v[64:65], v[66:67], v[140:141] op_sel_hi:[1,0,1]
	v_div_scale_f32 v62, s[0:1], v51, v51, 1.0
	v_rcp_f32_e32 v63, v62
	v_fma_f32 v52, v52, v66, v136
	v_fma_f32 v53, v53, v66, v137
	v_mul_f32_e32 v52, 0xbfb8aa3b, v52
	v_fma_f32 v64, -v62, v63, 1.0
	v_fmac_f32_e32 v63, v64, v63
	v_div_scale_f32 v64, vcc, 1.0, v51, 1.0
	v_mul_f32_e32 v65, v64, v63
	v_fma_f32 v68, -v62, v65, v64
	v_fmac_f32_e32 v65, v68, v63
	v_fma_f32 v62, -v62, v65, v64
	v_div_scale_f32 v64, s[0:1], v50, v50, 1.0
	v_rcp_f32_e32 v68, v64
	v_div_fmas_f32 v62, v62, v63, v65
	v_div_fixup_f32 v51, v62, v51, 1.0
	v_mul_f32_e32 v53, 0xbfb8aa3b, v53
	v_fma_f32 v62, -v64, v68, 1.0
	v_exp_f32_e32 v52, v52
	v_fmac_f32_e32 v68, v62, v68
	v_div_scale_f32 v62, vcc, 1.0, v50, 1.0
	v_exp_f32_e32 v53, v53
	v_mul_f32_e32 v63, v62, v68
	v_fma_f32 v65, -v64, v63, v62
	v_fmac_f32_e32 v63, v65, v68
	v_fma_f32 v62, -v64, v63, v62
	v_pk_add_f32 v[52:53], v[52:53], 1.0 op_sel_hi:[1,0]
	v_div_fmas_f32 v62, v62, v68, v63
	v_div_scale_f32 v63, s[0:1], v53, v53, 1.0
	v_rcp_f32_e32 v64, v63
	v_div_fixup_f32 v50, v62, v50, 1.0
	v_pk_mul_f32 v[60:61], v[60:61], v[50:51]
	v_pk_fma_f32 v[50:51], v[56:57], v[66:67], v[132:133] op_sel_hi:[1,0,1]
	v_fma_f32 v56, -v63, v64, 1.0
	v_fmac_f32_e32 v64, v56, v64
	v_div_scale_f32 v56, vcc, 1.0, v53, 1.0
	v_mul_f32_e32 v57, v56, v64
	v_fma_f32 v62, -v63, v57, v56
	v_fmac_f32_e32 v57, v62, v64
	v_div_scale_f32 v62, s[0:1], v52, v52, 1.0
	v_fma_f32 v56, -v63, v57, v56
	v_rcp_f32_e32 v63, v62
	v_div_fmas_f32 v56, v56, v64, v57
	v_div_fixup_f32 v53, v56, v53, 1.0
	v_fma_f32 v56, -v62, v63, 1.0
	v_fmac_f32_e32 v63, v56, v63
	v_div_scale_f32 v56, vcc, 1.0, v52, 1.0
	v_mul_f32_e32 v57, v56, v63
	v_fma_f32 v64, -v62, v57, v56
	v_fmac_f32_e32 v57, v64, v63
	v_fma_f32 v56, -v62, v57, v56
	v_div_fmas_f32 v56, v56, v63, v57
	v_div_fixup_f32 v52, v56, v52, 1.0
	v_pk_mul_f32 v[56:57], v[50:51], v[52:53]
	v_cvt_pk_bf16_f32 v52, v54, v55
	v_mad_i64_i32 v[54:55], s[0:1], v67, s54, v[114:115]
	v_cvt_pk_bf16_f32 v50, v58, v59
	v_cvt_pk_bf16_f32 v51, v60, v61
	v_cvt_pk_bf16_f32 v53, v56, v57
	v_lshl_add_u64 v[54:55], v[54:55], 0, v[116:117]
	global_store_dwordx4 v[54:55], v[50:53], off
	s_nop 1
	v_mov_b32_e32 v50, v221
	s_nop 0
	v_add_u32_e32 v51, 0x90, v166
	v_fmamk_f32 v50, v50, 0x3a800000, v187
	v_rsq_f32_e32 v50, v50
	s_nop 0
	v_fma_f32 v42, v42, v50, v142
	v_fma_f32 v43, v43, v50, v143
	v_mul_f32_e32 v42, 0xbfb8aa3b, v42
	v_mul_f32_e32 v43, 0xbfb8aa3b, v43
	v_exp_f32_e32 v42, v42
	v_exp_f32_e32 v43, v43
	v_fma_f32 v34, v34, v50, v134
	v_fma_f32 v35, v35, v50, v135
	v_mul_f32_e32 v34, 0xbfb8aa3b, v34
	v_pk_add_f32 v[42:43], v[42:43], 1.0 op_sel_hi:[1,0]
	v_mul_f32_e32 v35, 0xbfb8aa3b, v35
	v_div_scale_f32 v52, s[0:1], v43, v43, 1.0
	v_rcp_f32_e32 v53, v52
	v_exp_f32_e32 v34, v34
	v_exp_f32_e32 v35, v35
	v_pk_fma_f32 v[46:47], v[46:47], v[50:51], v[138:139] op_sel_hi:[1,0,1]
	v_fma_f32 v54, -v52, v53, 1.0
	v_fmac_f32_e32 v53, v54, v53
	v_div_scale_f32 v54, vcc, 1.0, v43, 1.0
	v_mul_f32_e32 v55, v54, v53
	v_fma_f32 v56, -v52, v55, v54
	v_fmac_f32_e32 v55, v56, v53
	v_fma_f32 v52, -v52, v55, v54
	v_div_scale_f32 v54, s[0:1], v42, v42, 1.0
	v_rcp_f32_e32 v56, v54
	v_div_fmas_f32 v52, v52, v53, v55
	v_div_fixup_f32 v43, v52, v43, 1.0
	v_pk_add_f32 v[34:35], v[34:35], 1.0 op_sel_hi:[1,0]
	v_fma_f32 v52, -v54, v56, 1.0
	v_fmac_f32_e32 v56, v52, v56
	v_div_scale_f32 v52, vcc, 1.0, v42, 1.0
	v_mul_f32_e32 v53, v52, v56
	v_fma_f32 v55, -v54, v53, v52
	v_fmac_f32_e32 v53, v55, v56
	v_fma_f32 v52, -v54, v53, v52
	v_div_fmas_f32 v52, v52, v56, v53
	v_div_scale_f32 v53, s[0:1], v35, v35, 1.0
	v_rcp_f32_e32 v54, v53
	v_div_fixup_f32 v42, v52, v42, 1.0
	v_pk_mul_f32 v[42:43], v[46:47], v[42:43]
	v_fma_f32 v44, v44, v50, v144
	v_fma_f32 v46, -v53, v54, 1.0
	v_fmac_f32_e32 v54, v46, v54
	v_div_scale_f32 v46, vcc, 1.0, v35, 1.0
	v_mul_f32_e32 v47, v46, v54
	v_fma_f32 v52, -v53, v47, v46
	v_fmac_f32_e32 v47, v52, v54
	v_div_scale_f32 v52, s[0:1], v34, v34, 1.0
	v_fma_f32 v46, -v53, v47, v46
	v_rcp_f32_e32 v53, v52
	v_div_fmas_f32 v46, v46, v54, v47
	v_div_fixup_f32 v35, v46, v35, 1.0
	v_fma_f32 v45, v45, v50, v145
	v_fma_f32 v46, -v52, v53, 1.0
	v_fmac_f32_e32 v53, v46, v53
	v_div_scale_f32 v46, vcc, 1.0, v34, 1.0
	v_mul_f32_e32 v47, v46, v53
	v_fma_f32 v54, -v52, v47, v46
	v_mul_f32_e32 v44, 0xbfb8aa3b, v44
	v_mul_f32_e32 v45, 0xbfb8aa3b, v45
	v_fmac_f32_e32 v47, v54, v53
	v_exp_f32_e32 v44, v44
	v_exp_f32_e32 v45, v45
	v_fma_f32 v46, -v52, v47, v46
	v_div_fmas_f32 v46, v46, v53, v47
	v_pk_fma_f32 v[38:39], v[38:39], v[50:51], v[130:131] op_sel_hi:[1,0,1]
	v_div_fixup_f32 v34, v46, v34, 1.0
	v_pk_mul_f32 v[38:39], v[38:39], v[34:35]
	v_pk_add_f32 v[34:35], v[44:45], 1.0 op_sel_hi:[1,0]
	v_pk_fma_f32 v[44:45], v[48:49], v[50:51], v[140:141] op_sel_hi:[1,0,1]
	v_div_scale_f32 v46, s[0:1], v35, v35, 1.0
	v_rcp_f32_e32 v47, v46
	v_fma_f32 v36, v36, v50, v136
	v_fma_f32 v37, v37, v50, v137
	v_mul_f32_e32 v36, 0xbfb8aa3b, v36
	v_fma_f32 v48, -v46, v47, 1.0
	v_fmac_f32_e32 v47, v48, v47
	v_div_scale_f32 v48, vcc, 1.0, v35, 1.0
	v_mul_f32_e32 v49, v48, v47
	v_fma_f32 v52, -v46, v49, v48
	v_fmac_f32_e32 v49, v52, v47
	v_fma_f32 v46, -v46, v49, v48
	v_div_scale_f32 v48, s[0:1], v34, v34, 1.0
	v_rcp_f32_e32 v52, v48
	v_div_fmas_f32 v46, v46, v47, v49
	v_div_fixup_f32 v35, v46, v35, 1.0
	v_mul_f32_e32 v37, 0xbfb8aa3b, v37
	v_fma_f32 v46, -v48, v52, 1.0
	v_exp_f32_e32 v36, v36
	v_fmac_f32_e32 v52, v46, v52
	v_div_scale_f32 v46, vcc, 1.0, v34, 1.0
	v_exp_f32_e32 v37, v37
	v_mul_f32_e32 v47, v46, v52
	v_fma_f32 v49, -v48, v47, v46
	v_fmac_f32_e32 v47, v49, v52
	v_fma_f32 v46, -v48, v47, v46
	v_pk_add_f32 v[36:37], v[36:37], 1.0 op_sel_hi:[1,0]
	v_div_fmas_f32 v46, v46, v52, v47
	v_div_scale_f32 v47, s[0:1], v37, v37, 1.0
	v_rcp_f32_e32 v48, v47
	v_div_fixup_f32 v34, v46, v34, 1.0
	v_pk_mul_f32 v[44:45], v[44:45], v[34:35]
	v_pk_fma_f32 v[34:35], v[40:41], v[50:51], v[132:133] op_sel_hi:[1,0,1]
	v_fma_f32 v40, -v47, v48, 1.0
	v_fmac_f32_e32 v48, v40, v48
	v_div_scale_f32 v40, vcc, 1.0, v37, 1.0
	v_mul_f32_e32 v41, v40, v48
	v_fma_f32 v46, -v47, v41, v40
	v_fmac_f32_e32 v41, v46, v48
	v_div_scale_f32 v46, s[0:1], v36, v36, 1.0
	v_fma_f32 v40, -v47, v41, v40
	v_rcp_f32_e32 v47, v46
	v_div_fmas_f32 v40, v40, v48, v41
	v_div_fixup_f32 v37, v40, v37, 1.0
	v_fma_f32 v40, -v46, v47, 1.0
	v_fmac_f32_e32 v47, v40, v47
	v_div_scale_f32 v40, vcc, 1.0, v36, 1.0
	v_mul_f32_e32 v41, v40, v47
	v_fma_f32 v48, -v46, v41, v40
	v_fmac_f32_e32 v41, v48, v47
	v_fma_f32 v40, -v46, v41, v40
	v_div_fmas_f32 v40, v40, v47, v41
	v_div_fixup_f32 v36, v40, v36, 1.0
	v_pk_mul_f32 v[40:41], v[34:35], v[36:37]
	v_cvt_pk_bf16_f32 v36, v38, v39
	v_mad_i64_i32 v[38:39], s[0:1], v51, s54, v[114:115]
	v_cvt_pk_bf16_f32 v34, v42, v43
	v_cvt_pk_bf16_f32 v35, v44, v45
	v_cvt_pk_bf16_f32 v37, v40, v41
	v_lshl_add_u64 v[38:39], v[38:39], 0, v[116:117]
	global_store_dwordx4 v[38:39], v[34:37], off
	s_nop 1
	v_mov_b32_e32 v34, v222
	s_nop 0
	v_add_u32_e32 v35, 0xa0, v166
	v_fmamk_f32 v34, v34, 0x3a800000, v187
	v_rsq_f32_e32 v34, v34
	s_nop 0
	v_fma_f32 v26, v26, v34, v142
	v_fma_f32 v27, v27, v34, v143
	v_mul_f32_e32 v26, 0xbfb8aa3b, v26
	v_mul_f32_e32 v27, 0xbfb8aa3b, v27
	v_exp_f32_e32 v26, v26
	v_exp_f32_e32 v27, v27
	v_fma_f32 v18, v18, v34, v134
	v_fma_f32 v19, v19, v34, v135
	v_mul_f32_e32 v18, 0xbfb8aa3b, v18
	v_pk_add_f32 v[26:27], v[26:27], 1.0 op_sel_hi:[1,0]
	v_mul_f32_e32 v19, 0xbfb8aa3b, v19
	v_div_scale_f32 v36, s[0:1], v27, v27, 1.0
	v_rcp_f32_e32 v37, v36
	v_exp_f32_e32 v18, v18
	v_exp_f32_e32 v19, v19
	v_pk_fma_f32 v[30:31], v[30:31], v[34:35], v[138:139] op_sel_hi:[1,0,1]
	v_fma_f32 v38, -v36, v37, 1.0
	v_fmac_f32_e32 v37, v38, v37
	v_div_scale_f32 v38, vcc, 1.0, v27, 1.0
	v_mul_f32_e32 v39, v38, v37
	v_fma_f32 v40, -v36, v39, v38
	v_fmac_f32_e32 v39, v40, v37
	v_fma_f32 v36, -v36, v39, v38
	v_div_scale_f32 v38, s[0:1], v26, v26, 1.0
	v_rcp_f32_e32 v40, v38
	v_div_fmas_f32 v36, v36, v37, v39
	v_div_fixup_f32 v27, v36, v27, 1.0
	v_pk_add_f32 v[18:19], v[18:19], 1.0 op_sel_hi:[1,0]
	v_fma_f32 v36, -v38, v40, 1.0
	v_fmac_f32_e32 v40, v36, v40
	v_div_scale_f32 v36, vcc, 1.0, v26, 1.0
	v_mul_f32_e32 v37, v36, v40
	v_fma_f32 v39, -v38, v37, v36
	v_fmac_f32_e32 v37, v39, v40
	v_fma_f32 v36, -v38, v37, v36
	v_div_fmas_f32 v36, v36, v40, v37
	v_div_scale_f32 v37, s[0:1], v19, v19, 1.0
	v_rcp_f32_e32 v38, v37
	v_div_fixup_f32 v26, v36, v26, 1.0
	v_pk_mul_f32 v[26:27], v[30:31], v[26:27]
	v_fma_f32 v28, v28, v34, v144
	v_fma_f32 v30, -v37, v38, 1.0
	v_fmac_f32_e32 v38, v30, v38
	v_div_scale_f32 v30, vcc, 1.0, v19, 1.0
	v_mul_f32_e32 v31, v30, v38
	v_fma_f32 v36, -v37, v31, v30
	v_fmac_f32_e32 v31, v36, v38
	v_div_scale_f32 v36, s[0:1], v18, v18, 1.0
	v_fma_f32 v30, -v37, v31, v30
	v_rcp_f32_e32 v37, v36
	v_div_fmas_f32 v30, v30, v38, v31
	v_div_fixup_f32 v19, v30, v19, 1.0
	v_fma_f32 v29, v29, v34, v145
	v_fma_f32 v30, -v36, v37, 1.0
	v_fmac_f32_e32 v37, v30, v37
	v_div_scale_f32 v30, vcc, 1.0, v18, 1.0
	v_mul_f32_e32 v31, v30, v37
	v_fma_f32 v38, -v36, v31, v30
	v_mul_f32_e32 v28, 0xbfb8aa3b, v28
	v_mul_f32_e32 v29, 0xbfb8aa3b, v29
	v_fmac_f32_e32 v31, v38, v37
	v_exp_f32_e32 v28, v28
	v_exp_f32_e32 v29, v29
	v_fma_f32 v30, -v36, v31, v30
	v_div_fmas_f32 v30, v30, v37, v31
	v_pk_fma_f32 v[22:23], v[22:23], v[34:35], v[130:131] op_sel_hi:[1,0,1]
	v_div_fixup_f32 v18, v30, v18, 1.0
	v_pk_mul_f32 v[22:23], v[22:23], v[18:19]
	v_pk_add_f32 v[18:19], v[28:29], 1.0 op_sel_hi:[1,0]
	v_pk_fma_f32 v[28:29], v[32:33], v[34:35], v[140:141] op_sel_hi:[1,0,1]
	v_div_scale_f32 v30, s[0:1], v19, v19, 1.0
	v_rcp_f32_e32 v31, v30
	v_fma_f32 v20, v20, v34, v136
	v_fma_f32 v21, v21, v34, v137
	v_mul_f32_e32 v20, 0xbfb8aa3b, v20
	v_fma_f32 v32, -v30, v31, 1.0
	v_fmac_f32_e32 v31, v32, v31
	v_div_scale_f32 v32, vcc, 1.0, v19, 1.0
	v_mul_f32_e32 v33, v32, v31
	v_fma_f32 v36, -v30, v33, v32
	v_fmac_f32_e32 v33, v36, v31
	v_fma_f32 v30, -v30, v33, v32
	v_div_scale_f32 v32, s[0:1], v18, v18, 1.0
	v_rcp_f32_e32 v36, v32
	v_div_fmas_f32 v30, v30, v31, v33
	v_div_fixup_f32 v19, v30, v19, 1.0
	v_mul_f32_e32 v21, 0xbfb8aa3b, v21
	v_fma_f32 v30, -v32, v36, 1.0
	v_exp_f32_e32 v20, v20
	v_fmac_f32_e32 v36, v30, v36
	v_div_scale_f32 v30, vcc, 1.0, v18, 1.0
	v_exp_f32_e32 v21, v21
	v_mul_f32_e32 v31, v30, v36
	v_fma_f32 v33, -v32, v31, v30
	v_fmac_f32_e32 v31, v33, v36
	v_fma_f32 v30, -v32, v31, v30
	v_pk_add_f32 v[20:21], v[20:21], 1.0 op_sel_hi:[1,0]
	v_div_fmas_f32 v30, v30, v36, v31
	v_div_scale_f32 v31, s[0:1], v21, v21, 1.0
	v_rcp_f32_e32 v32, v31
	v_div_fixup_f32 v18, v30, v18, 1.0
	v_pk_mul_f32 v[28:29], v[28:29], v[18:19]
	v_pk_fma_f32 v[18:19], v[24:25], v[34:35], v[132:133] op_sel_hi:[1,0,1]
	v_fma_f32 v24, -v31, v32, 1.0
	v_fmac_f32_e32 v32, v24, v32
	v_div_scale_f32 v24, vcc, 1.0, v21, 1.0
	v_mul_f32_e32 v25, v24, v32
	v_fma_f32 v30, -v31, v25, v24
	v_fmac_f32_e32 v25, v30, v32
	v_div_scale_f32 v30, s[0:1], v20, v20, 1.0
	v_fma_f32 v24, -v31, v25, v24
	v_rcp_f32_e32 v31, v30
	v_div_fmas_f32 v24, v24, v32, v25
	v_div_fixup_f32 v21, v24, v21, 1.0
	v_fma_f32 v24, -v30, v31, 1.0
	v_fmac_f32_e32 v31, v24, v31
	v_div_scale_f32 v24, vcc, 1.0, v20, 1.0
	v_mul_f32_e32 v25, v24, v31
	v_fma_f32 v32, -v30, v25, v24
	v_fmac_f32_e32 v25, v32, v31
	v_fma_f32 v24, -v30, v25, v24
	v_div_fmas_f32 v24, v24, v31, v25
	v_div_fixup_f32 v20, v24, v20, 1.0
	v_pk_mul_f32 v[24:25], v[18:19], v[20:21]
	v_cvt_pk_bf16_f32 v20, v22, v23
	v_mad_i64_i32 v[22:23], s[0:1], v35, s54, v[114:115]
	v_cvt_pk_bf16_f32 v18, v26, v27
	v_cvt_pk_bf16_f32 v19, v28, v29
	v_cvt_pk_bf16_f32 v21, v24, v25
	v_lshl_add_u64 v[22:23], v[22:23], 0, v[116:117]
	global_store_dwordx4 v[22:23], v[18:21], off
	s_nop 1
	v_mov_b32_e32 v18, v223
	s_nop 0
	v_add_u32_e32 v19, 0xb0, v166
	v_fmamk_f32 v18, v18, 0x3a800000, v187
	v_rsq_f32_e32 v18, v18
	s_nop 0
	v_fma_f32 v10, v10, v18, v142
	v_fma_f32 v11, v11, v18, v143
	v_mul_f32_e32 v10, 0xbfb8aa3b, v10
	v_mul_f32_e32 v11, 0xbfb8aa3b, v11
	v_exp_f32_e32 v10, v10
	v_exp_f32_e32 v11, v11
	v_fma_f32 v2, v2, v18, v134
	v_fma_f32 v3, v3, v18, v135
	v_mul_f32_e32 v2, 0xbfb8aa3b, v2
	v_pk_add_f32 v[10:11], v[10:11], 1.0 op_sel_hi:[1,0]
	v_mul_f32_e32 v3, 0xbfb8aa3b, v3
	v_div_scale_f32 v20, s[0:1], v11, v11, 1.0
	v_rcp_f32_e32 v21, v20
	v_exp_f32_e32 v2, v2
	v_exp_f32_e32 v3, v3
	v_pk_fma_f32 v[14:15], v[14:15], v[18:19], v[138:139] op_sel_hi:[1,0,1]
	v_fma_f32 v22, -v20, v21, 1.0
	v_fmac_f32_e32 v21, v22, v21
	v_div_scale_f32 v22, vcc, 1.0, v11, 1.0
	v_mul_f32_e32 v23, v22, v21
	v_fma_f32 v24, -v20, v23, v22
	v_fmac_f32_e32 v23, v24, v21
	v_fma_f32 v20, -v20, v23, v22
	v_div_scale_f32 v22, s[0:1], v10, v10, 1.0
	v_rcp_f32_e32 v24, v22
	v_div_fmas_f32 v20, v20, v21, v23
	v_div_fixup_f32 v11, v20, v11, 1.0
	v_pk_add_f32 v[2:3], v[2:3], 1.0 op_sel_hi:[1,0]
	v_fma_f32 v20, -v22, v24, 1.0
	v_fmac_f32_e32 v24, v20, v24
	v_div_scale_f32 v20, vcc, 1.0, v10, 1.0
	v_mul_f32_e32 v21, v20, v24
	v_fma_f32 v23, -v22, v21, v20
	v_fmac_f32_e32 v21, v23, v24
	v_fma_f32 v20, -v22, v21, v20
	v_div_fmas_f32 v20, v20, v24, v21
	v_div_scale_f32 v21, s[0:1], v3, v3, 1.0
	v_rcp_f32_e32 v22, v21
	v_div_fixup_f32 v10, v20, v10, 1.0
	v_pk_mul_f32 v[10:11], v[14:15], v[10:11]
	v_fma_f32 v12, v12, v18, v144
	v_fma_f32 v14, -v21, v22, 1.0
	v_fmac_f32_e32 v22, v14, v22
	v_div_scale_f32 v14, vcc, 1.0, v3, 1.0
	v_mul_f32_e32 v15, v14, v22
	v_fma_f32 v20, -v21, v15, v14
	v_fmac_f32_e32 v15, v20, v22
	v_div_scale_f32 v20, s[0:1], v2, v2, 1.0
	v_fma_f32 v14, -v21, v15, v14
	v_rcp_f32_e32 v21, v20
	v_div_fmas_f32 v14, v14, v22, v15
	v_div_fixup_f32 v3, v14, v3, 1.0
	v_fmac_f32_e32 v145, v13, v18
	v_fma_f32 v14, -v20, v21, 1.0
	v_fmac_f32_e32 v21, v14, v21
	v_div_scale_f32 v14, vcc, 1.0, v2, 1.0
	v_mul_f32_e32 v15, v14, v21
	v_fma_f32 v22, -v20, v15, v14
	v_mul_f32_e32 v12, 0xbfb8aa3b, v12
	v_mul_f32_e32 v13, 0xbfb8aa3b, v145
	v_fmac_f32_e32 v15, v22, v21
	v_exp_f32_e32 v12, v12
	v_exp_f32_e32 v13, v13
	v_fma_f32 v14, -v20, v15, v14
	v_div_fmas_f32 v14, v14, v21, v15
	v_pk_fma_f32 v[6:7], v[6:7], v[18:19], v[130:131] op_sel_hi:[1,0,1]
	v_div_fixup_f32 v2, v14, v2, 1.0
	v_pk_mul_f32 v[6:7], v[6:7], v[2:3]
	v_pk_add_f32 v[2:3], v[12:13], 1.0 op_sel_hi:[1,0]
	v_pk_fma_f32 v[12:13], v[16:17], v[18:19], v[140:141] op_sel_hi:[1,0,1]
	v_div_scale_f32 v14, s[0:1], v3, v3, 1.0
	v_rcp_f32_e32 v15, v14
	v_fma_f32 v4, v4, v18, v136
	v_fmac_f32_e32 v137, v5, v18
	v_mul_f32_e32 v4, 0xbfb8aa3b, v4
	v_fma_f32 v16, -v14, v15, 1.0
	v_fmac_f32_e32 v15, v16, v15
	v_div_scale_f32 v16, vcc, 1.0, v3, 1.0
	v_mul_f32_e32 v17, v16, v15
	v_fma_f32 v20, -v14, v17, v16
	v_fmac_f32_e32 v17, v20, v15
	v_fma_f32 v14, -v14, v17, v16
	v_div_scale_f32 v16, s[0:1], v2, v2, 1.0
	v_rcp_f32_e32 v20, v16
	v_div_fmas_f32 v14, v14, v15, v17
	v_div_fixup_f32 v3, v14, v3, 1.0
	v_mul_f32_e32 v5, 0xbfb8aa3b, v137
	v_fma_f32 v14, -v16, v20, 1.0
	v_exp_f32_e32 v4, v4
	v_fmac_f32_e32 v20, v14, v20
	v_div_scale_f32 v14, vcc, 1.0, v2, 1.0
	v_exp_f32_e32 v5, v5
	v_mul_f32_e32 v15, v14, v20
	v_fma_f32 v17, -v16, v15, v14
	v_fmac_f32_e32 v15, v17, v20
	v_fma_f32 v14, -v16, v15, v14
	v_pk_add_f32 v[4:5], v[4:5], 1.0 op_sel_hi:[1,0]
	v_div_fmas_f32 v14, v14, v20, v15
	v_div_scale_f32 v15, s[0:1], v5, v5, 1.0
	v_rcp_f32_e32 v16, v15
	v_div_fixup_f32 v2, v14, v2, 1.0
	v_pk_mul_f32 v[12:13], v[12:13], v[2:3]
	v_pk_fma_f32 v[2:3], v[8:9], v[18:19], v[132:133] op_sel_hi:[1,0,1]
	v_fma_f32 v8, -v15, v16, 1.0
	v_fmac_f32_e32 v16, v8, v16
	v_div_scale_f32 v8, vcc, 1.0, v5, 1.0
	v_mul_f32_e32 v9, v8, v16
	v_fma_f32 v14, -v15, v9, v8
	v_fmac_f32_e32 v9, v14, v16
	v_div_scale_f32 v14, s[0:1], v4, v4, 1.0
	v_fma_f32 v8, -v15, v9, v8
	v_rcp_f32_e32 v15, v14
	v_div_fmas_f32 v8, v8, v16, v9
	v_div_fixup_f32 v5, v8, v5, 1.0
	v_fma_f32 v8, -v14, v15, 1.0
	v_fmac_f32_e32 v15, v8, v15
	v_div_scale_f32 v8, vcc, 1.0, v4, 1.0
	v_mul_f32_e32 v9, v8, v15
	v_fma_f32 v16, -v14, v9, v8
	v_fmac_f32_e32 v9, v16, v15
	v_fma_f32 v8, -v14, v9, v8
	v_div_fmas_f32 v8, v8, v15, v9
	v_div_fixup_f32 v4, v8, v4, 1.0
	v_pk_mul_f32 v[8:9], v[2:3], v[4:5]
	v_cvt_pk_bf16_f32 v4, v6, v7
	v_mad_i64_i32 v[6:7], s[0:1], v19, s54, v[114:115]
	v_cvt_pk_bf16_f32 v2, v10, v11
	v_cvt_pk_bf16_f32 v3, v12, v13
	v_cvt_pk_bf16_f32 v5, v8, v9
	v_lshl_add_u64 v[6:7], v[6:7], 0, v[116:117]
	global_store_dwordx4 v[6:7], v[2:5], off
	s_andn2_b64 vcc, exec, s[2:3]
	s_mov_b64 s[0:1], -1
	s_cbranch_vccnz .LBB0_155
